# first grid barrier: the 16 per-XCD count loads of the discovery pass are requested together (one round trip instead of 15 serial ones)
# speedup vs baseline: 1.0156x; 1.0026x over previous
; __device__ __forceinline__ unsigned xb_ld(unsigned* p)              { return __hip_atomic_load(p, __ATOMIC_RELAXED, __HIP_MEMORY_SCOPE_AGENT); }
; __device__ __forceinline__ void xcd_barrier_complete(unsigned* bar, unsigned x, unsigned& nloc, unsigned& nx) {
;     ...
;     for (;;) {
;         sum = 0u; cnt = 0u; mine = 0u;
; #pragma unroll
;         for (unsigned j = 0; j < 16; ++j) { const unsigned c = xb_ld(&bar[XB_XCNT(j)]); sum += c; cnt += (c > 0u) ? 1u : 0u; mine = (j == x) ? c : mine; }
;         if (sum == G) break;
;         __builtin_amdgcn_s_sleep(1);
;         if ((++sp & 255u) == 0u) { if (xb_ld(&bar[XB_TMO])) break; if (sp > XB_SPIN_CAP) { atomicAdd(&bar[XB_TMO], 1u); break; } }
;     }
.LBB0_2246:
	v_readlane_b32 s2, v253, 6
	v_readlane_b32 s3, v253, 7
	global_load_dword v1, v36, s[92:93] sc1
	s_waitcnt lgkmcnt(0)
	global_load_dword v0, v36, s[94:95] sc1
	s_mov_b64 s[4:5], -1
	s_nop 1
	s_nop 0
	global_load_dword v2, v36, s[2:3] sc1
	v_readlane_b32 s2, v253, 8
	v_readlane_b32 s3, v253, 9
	s_nop 1
	s_nop 0
	s_nop 2
	global_load_dword v3, v36, s[2:3] sc1
	v_readlane_b32 s2, v253, 10
	v_readlane_b32 s3, v253, 11
	s_nop 1
	s_nop 0
	s_nop 2
	global_load_dword v4, v36, s[2:3] sc1
	v_readlane_b32 s2, v253, 12
	v_readlane_b32 s3, v253, 13
	s_nop 1
	s_nop 0
	s_nop 2
	global_load_dword v5, v36, s[2:3] sc1
	v_readlane_b32 s2, v253, 14
	v_readlane_b32 s3, v253, 15
	s_nop 1
	s_nop 0
	s_nop 2
	global_load_dword v6, v36, s[2:3] sc1
	v_readlane_b32 s2, v253, 16
	v_readlane_b32 s3, v253, 17
	s_nop 1
	s_nop 0
	s_nop 2
	global_load_dword v7, v36, s[2:3] sc1
	v_readlane_b32 s2, v253, 18
	v_readlane_b32 s3, v253, 19
	s_nop 1
	s_nop 0
	s_nop 2
	global_load_dword v8, v36, s[2:3] sc1
	v_readlane_b32 s2, v253, 20
	v_readlane_b32 s3, v253, 21
	s_nop 1
	s_nop 0
	s_nop 2
	global_load_dword v9, v36, s[2:3] sc1
	v_readlane_b32 s2, v253, 22
	v_readlane_b32 s3, v253, 23
	s_nop 1
	s_nop 0
	s_nop 2
	global_load_dword v10, v36, s[2:3] sc1
	v_readlane_b32 s2, v253, 24
	v_readlane_b32 s3, v253, 25
	s_nop 1
	s_nop 0
	s_nop 2
	global_load_dword v11, v36, s[2:3] sc1
	v_readlane_b32 s2, v253, 26
	v_readlane_b32 s3, v253, 27
	s_nop 1
	s_nop 0
	s_nop 2
	global_load_dword v12, v36, s[2:3] sc1
	v_readlane_b32 s2, v253, 28
	v_readlane_b32 s3, v253, 29
	s_nop 1
	s_nop 0
	s_nop 2
	global_load_dword v13, v36, s[2:3] sc1
	v_readlane_b32 s2, v253, 30
	v_readlane_b32 s3, v253, 31
	s_nop 1
	s_nop 0
	s_nop 2
	global_load_dword v14, v36, s[2:3] sc1
	v_readlane_b32 s2, v253, 32
	v_readlane_b32 s3, v253, 33
	s_nop 1
	s_nop 0
	s_nop 2
	global_load_dword v15, v36, s[2:3] sc1
	s_mov_b64 s[2:3], -1
	s_nop 1
	s_nop 0
	s_waitcnt vmcnt(0)
	v_add_u32_e32 v16, v0, v1
	v_add_u32_e32 v16, v16, v2
	v_add_u32_e32 v16, v16, v3
	v_add_u32_e32 v16, v16, v4
	v_add_u32_e32 v16, v16, v5
	v_add_u32_e32 v16, v16, v6
	v_add_u32_e32 v16, v16, v7
	v_add_u32_e32 v16, v16, v8
	v_add_u32_e32 v16, v16, v9
	v_add_u32_e32 v16, v16, v10
	v_add_u32_e32 v16, v16, v11
	v_add_u32_e32 v16, v16, v12
	v_add_u32_e32 v16, v16, v13
	v_add_u32_e32 v16, v16, v14
	v_add_u32_e32 v16, v16, v15
	v_cmp_eq_u32_e32 vcc, s63, v16
	s_cbranch_vccnz .LBB0_2245
	s_and_b32 s2, s10, 0xff
	s_cmp_eq_u32 s2, 0
	s_mov_b64 s[2:3], -1
	s_mov_b64 s[6:7], -1
	s_sleep 1
	s_cbranch_scc0 .LBB0_2250
	v_readlane_b32 s2, v253, 4
	v_readlane_b32 s3, v253, 5
	s_nop 4
	global_load_dword v16, v36, s[2:3] sc1
	s_waitcnt vmcnt(0)
	v_cmp_eq_u32_e32 vcc, 0, v16
	s_cbranch_vccnz .LBB0_2252
	s_mov_b64 s[6:7], 0
	s_mov_b64 s[2:3], -1
